# E18: setup adaLN GEMV: weight loads software-pipelined 32 deep via SGPR base, sv double-buffered from LDS (on top of E17b)
# speedup vs baseline: 1.0030x; 1.0030x over previous
; #define P (*get_params())
; template <class PT> __device__ __forceinline__ void setup_phase(const PT& P, float* X, float* MOD, float* ROPE, float* LB, float* SCAL, char* lds) {
;     ...
;       const int l = item / 96, n = (item % 96) * 64 + lane; float a0 = 0.f, a1 = 0.f;
;       const float* w = P.ada_w + ((size_t)l * 1024 + wid * 128) * 6144 + n;
; #pragma unroll 8
;       for (int k = 0; k < 128; ++k) { const float wv = w[(size_t)k * 6144]; a0 = fmaf(sv[wid * 128 + k], wv, a0); a1 = fmaf(sv[1024 + wid * 128 + k], wv, a1); }
.LBB0_12:
	v_readfirstlane_b32 s30, v12
	v_readfirstlane_b32 s31, v13
	v_lshlrev_b32_e32 v52, 2, v1
	s_nop 4
	ds_read_b128 v[96:99], v17
	ds_read_b128 v[100:103], v17 offset:16
	ds_read_b128 v[104:107], v17 offset:32
	ds_read_b128 v[108:111], v17 offset:48
	ds_read_b128 v[112:115], v17 offset:4096
	ds_read_b128 v[116:119], v17 offset:4112
	ds_read_b128 v[120:123], v17 offset:4128
	ds_read_b128 v[124:127], v17 offset:4144
	global_load_dword v64, v52, s[30:31]
	s_add_u32 s30, s30, 0x6000
	s_addc_u32 s31, s31, 0
	global_load_dword v65, v52, s[30:31]
	s_add_u32 s30, s30, 0x6000
	s_addc_u32 s31, s31, 0
	global_load_dword v66, v52, s[30:31]
	s_add_u32 s30, s30, 0x6000
	s_addc_u32 s31, s31, 0
	global_load_dword v67, v52, s[30:31]
	s_add_u32 s30, s30, 0x6000
	s_addc_u32 s31, s31, 0
	global_load_dword v68, v52, s[30:31]
	s_add_u32 s30, s30, 0x6000
	s_addc_u32 s31, s31, 0
	global_load_dword v69, v52, s[30:31]
	s_add_u32 s30, s30, 0x6000
	s_addc_u32 s31, s31, 0
	global_load_dword v70, v52, s[30:31]
	s_add_u32 s30, s30, 0x6000
	s_addc_u32 s31, s31, 0
	global_load_dword v71, v52, s[30:31]
	s_add_u32 s30, s30, 0x6000
	s_addc_u32 s31, s31, 0
	global_load_dword v72, v52, s[30:31]
	s_add_u32 s30, s30, 0x6000
	s_addc_u32 s31, s31, 0
	global_load_dword v73, v52, s[30:31]
	s_add_u32 s30, s30, 0x6000
	s_addc_u32 s31, s31, 0
	global_load_dword v74, v52, s[30:31]
	s_add_u32 s30, s30, 0x6000
	s_addc_u32 s31, s31, 0
	global_load_dword v75, v52, s[30:31]
	s_add_u32 s30, s30, 0x6000
	s_addc_u32 s31, s31, 0
	global_load_dword v76, v52, s[30:31]
	s_add_u32 s30, s30, 0x6000
	s_addc_u32 s31, s31, 0
	global_load_dword v77, v52, s[30:31]
	s_add_u32 s30, s30, 0x6000
	s_addc_u32 s31, s31, 0
	global_load_dword v78, v52, s[30:31]
	s_add_u32 s30, s30, 0x6000
	s_addc_u32 s31, s31, 0
	global_load_dword v79, v52, s[30:31]
	s_add_u32 s30, s30, 0x6000
	s_addc_u32 s31, s31, 0
	global_load_dword v80, v52, s[30:31]
	s_add_u32 s30, s30, 0x6000
	s_addc_u32 s31, s31, 0
	global_load_dword v81, v52, s[30:31]
	s_add_u32 s30, s30, 0x6000
	s_addc_u32 s31, s31, 0
	global_load_dword v82, v52, s[30:31]
	s_add_u32 s30, s30, 0x6000
	s_addc_u32 s31, s31, 0
	global_load_dword v83, v52, s[30:31]
	s_add_u32 s30, s30, 0x6000
	s_addc_u32 s31, s31, 0
	global_load_dword v84, v52, s[30:31]
	s_add_u32 s30, s30, 0x6000
	s_addc_u32 s31, s31, 0
	global_load_dword v85, v52, s[30:31]
	s_add_u32 s30, s30, 0x6000
	s_addc_u32 s31, s31, 0
	global_load_dword v86, v52, s[30:31]
	s_add_u32 s30, s30, 0x6000
	s_addc_u32 s31, s31, 0
	global_load_dword v87, v52, s[30:31]
	s_add_u32 s30, s30, 0x6000
	s_addc_u32 s31, s31, 0
	global_load_dword v88, v52, s[30:31]
	s_add_u32 s30, s30, 0x6000
	s_addc_u32 s31, s31, 0
	global_load_dword v89, v52, s[30:31]
	s_add_u32 s30, s30, 0x6000
	s_addc_u32 s31, s31, 0
	global_load_dword v90, v52, s[30:31]
	s_add_u32 s30, s30, 0x6000
	s_addc_u32 s31, s31, 0
	global_load_dword v91, v52, s[30:31]
	s_add_u32 s30, s30, 0x6000
	s_addc_u32 s31, s31, 0
	global_load_dword v92, v52, s[30:31]
	s_add_u32 s30, s30, 0x6000
	s_addc_u32 s31, s31, 0
	global_load_dword v93, v52, s[30:31]
	s_add_u32 s30, s30, 0x6000
	s_addc_u32 s31, s31, 0
	global_load_dword v94, v52, s[30:31]
	s_add_u32 s30, s30, 0x6000
	s_addc_u32 s31, s31, 0
	global_load_dword v95, v52, s[30:31]
	s_add_u32 s30, s30, 0x6000
	s_addc_u32 s31, s31, 0
	ds_read_b128 v[128:131], v17 offset:64
	ds_read_b128 v[132:135], v17 offset:80
	ds_read_b128 v[136:139], v17 offset:96
	ds_read_b128 v[140:143], v17 offset:112
	ds_read_b128 v[148:151], v17 offset:4160
	ds_read_b128 v[152:155], v17 offset:4176
	ds_read_b128 v[156:159], v17 offset:4192
	ds_read_b128 v[160:163], v17 offset:4208
	s_waitcnt lgkmcnt(8)
	s_waitcnt vmcnt(31)
	v_fmac_f32_e32 v14, v96, v64
	v_fmac_f32_e32 v15, v112, v64
	global_load_dword v64, v52, s[30:31]
	s_add_u32 s30, s30, 0x6000
	s_addc_u32 s31, s31, 0
	s_waitcnt vmcnt(31)
	v_fmac_f32_e32 v14, v97, v65
	v_fmac_f32_e32 v15, v113, v65
	global_load_dword v65, v52, s[30:31]
	s_add_u32 s30, s30, 0x6000
	s_addc_u32 s31, s31, 0
	s_waitcnt vmcnt(31)
	v_fmac_f32_e32 v14, v98, v66
	v_fmac_f32_e32 v15, v114, v66
	global_load_dword v66, v52, s[30:31]
	s_add_u32 s30, s30, 0x6000
	s_addc_u32 s31, s31, 0
	s_waitcnt vmcnt(31)
	v_fmac_f32_e32 v14, v99, v67
	v_fmac_f32_e32 v15, v115, v67
	global_load_dword v67, v52, s[30:31]
	s_add_u32 s30, s30, 0x6000
	s_addc_u32 s31, s31, 0
	s_waitcnt vmcnt(31)
	v_fmac_f32_e32 v14, v100, v68
	v_fmac_f32_e32 v15, v116, v68
	global_load_dword v68, v52, s[30:31]
	s_add_u32 s30, s30, 0x6000
	s_addc_u32 s31, s31, 0
	s_waitcnt vmcnt(31)
	v_fmac_f32_e32 v14, v101, v69
	v_fmac_f32_e32 v15, v117, v69
	global_load_dword v69, v52, s[30:31]
	s_add_u32 s30, s30, 0x6000
	s_addc_u32 s31, s31, 0
	s_waitcnt vmcnt(31)
	v_fmac_f32_e32 v14, v102, v70
	v_fmac_f32_e32 v15, v118, v70
	global_load_dword v70, v52, s[30:31]
	s_add_u32 s30, s30, 0x6000
	s_addc_u32 s31, s31, 0
	s_waitcnt vmcnt(31)
	v_fmac_f32_e32 v14, v103, v71
	v_fmac_f32_e32 v15, v119, v71
	global_load_dword v71, v52, s[30:31]
	s_add_u32 s30, s30, 0x6000
	s_addc_u32 s31, s31, 0
	s_waitcnt vmcnt(31)
	v_fmac_f32_e32 v14, v104, v72
	v_fmac_f32_e32 v15, v120, v72
	global_load_dword v72, v52, s[30:31]
	s_add_u32 s30, s30, 0x6000
	s_addc_u32 s31, s31, 0
	s_waitcnt vmcnt(31)
	v_fmac_f32_e32 v14, v105, v73
	v_fmac_f32_e32 v15, v121, v73
	global_load_dword v73, v52, s[30:31]
	s_add_u32 s30, s30, 0x6000
	s_addc_u32 s31, s31, 0
	s_waitcnt vmcnt(31)
	v_fmac_f32_e32 v14, v106, v74
	v_fmac_f32_e32 v15, v122, v74
	global_load_dword v74, v52, s[30:31]
	s_add_u32 s30, s30, 0x6000
	s_addc_u32 s31, s31, 0
	s_waitcnt vmcnt(31)
; template <class PT> __device__ __forceinline__ void setup_phase(const PT& P, float* X, float* MOD, float* ROPE, float* LB, float* SCAL, char* lds) {
;     ...
; #pragma unroll 8
;       for (int k = 0; k < 128; ++k) { const float wv = w[(size_t)k * 6144]; a0 = fmaf(sv[wid * 128 + k], wv, a0); a1 = fmaf(sv[1024 + wid * 128 + k], wv, a1); }
	v_fmac_f32_e32 v14, v107, v75
	v_fmac_f32_e32 v15, v123, v75
	global_load_dword v75, v52, s[30:31]
	s_add_u32 s30, s30, 0x6000
	s_addc_u32 s31, s31, 0
	s_waitcnt vmcnt(31)
	v_fmac_f32_e32 v14, v108, v76
	v_fmac_f32_e32 v15, v124, v76
	global_load_dword v76, v52, s[30:31]
	s_add_u32 s30, s30, 0x6000
	s_addc_u32 s31, s31, 0
	s_waitcnt vmcnt(31)
	v_fmac_f32_e32 v14, v109, v77
	v_fmac_f32_e32 v15, v125, v77
	global_load_dword v77, v52, s[30:31]
	s_add_u32 s30, s30, 0x6000
	s_addc_u32 s31, s31, 0
	s_waitcnt vmcnt(31)
	v_fmac_f32_e32 v14, v110, v78
	v_fmac_f32_e32 v15, v126, v78
	global_load_dword v78, v52, s[30:31]
	s_add_u32 s30, s30, 0x6000
	s_addc_u32 s31, s31, 0
	s_waitcnt vmcnt(31)
	v_fmac_f32_e32 v14, v111, v79
	v_fmac_f32_e32 v15, v127, v79
	global_load_dword v79, v52, s[30:31]
	s_add_u32 s30, s30, 0x6000
	s_addc_u32 s31, s31, 0
	ds_read_b128 v[96:99], v17 offset:128
	ds_read_b128 v[100:103], v17 offset:144
	ds_read_b128 v[104:107], v17 offset:160
	ds_read_b128 v[108:111], v17 offset:176
	ds_read_b128 v[112:115], v17 offset:4224
	ds_read_b128 v[116:119], v17 offset:4240
	ds_read_b128 v[120:123], v17 offset:4256
	ds_read_b128 v[124:127], v17 offset:4272
	s_waitcnt lgkmcnt(8)
	s_waitcnt vmcnt(31)
	v_fmac_f32_e32 v14, v128, v80
	v_fmac_f32_e32 v15, v148, v80
	global_load_dword v80, v52, s[30:31]
	s_add_u32 s30, s30, 0x6000
	s_addc_u32 s31, s31, 0
	s_waitcnt vmcnt(31)
	v_fmac_f32_e32 v14, v129, v81
	v_fmac_f32_e32 v15, v149, v81
	global_load_dword v81, v52, s[30:31]
	s_add_u32 s30, s30, 0x6000
	s_addc_u32 s31, s31, 0
	s_waitcnt vmcnt(31)
	v_fmac_f32_e32 v14, v130, v82
	v_fmac_f32_e32 v15, v150, v82
	global_load_dword v82, v52, s[30:31]
	s_add_u32 s30, s30, 0x6000
	s_addc_u32 s31, s31, 0
	s_waitcnt vmcnt(31)
	v_fmac_f32_e32 v14, v131, v83
	v_fmac_f32_e32 v15, v151, v83
	global_load_dword v83, v52, s[30:31]
	s_add_u32 s30, s30, 0x6000
	s_addc_u32 s31, s31, 0
	s_waitcnt vmcnt(31)
	v_fmac_f32_e32 v14, v132, v84
	v_fmac_f32_e32 v15, v152, v84
	global_load_dword v84, v52, s[30:31]
	s_add_u32 s30, s30, 0x6000
	s_addc_u32 s31, s31, 0
	s_waitcnt vmcnt(31)
	v_fmac_f32_e32 v14, v133, v85
	v_fmac_f32_e32 v15, v153, v85
	global_load_dword v85, v52, s[30:31]
	s_add_u32 s30, s30, 0x6000
	s_addc_u32 s31, s31, 0
	s_waitcnt vmcnt(31)
	v_fmac_f32_e32 v14, v134, v86
	v_fmac_f32_e32 v15, v154, v86
	global_load_dword v86, v52, s[30:31]
	s_add_u32 s30, s30, 0x6000
	s_addc_u32 s31, s31, 0
	s_waitcnt vmcnt(31)
	v_fmac_f32_e32 v14, v135, v87
	v_fmac_f32_e32 v15, v155, v87
	global_load_dword v87, v52, s[30:31]
	s_add_u32 s30, s30, 0x6000
	s_addc_u32 s31, s31, 0
	s_waitcnt vmcnt(31)
	v_fmac_f32_e32 v14, v136, v88
	v_fmac_f32_e32 v15, v156, v88
	global_load_dword v88, v52, s[30:31]
	s_add_u32 s30, s30, 0x6000
	s_addc_u32 s31, s31, 0
	s_waitcnt vmcnt(31)
	v_fmac_f32_e32 v14, v137, v89
	v_fmac_f32_e32 v15, v157, v89
	global_load_dword v89, v52, s[30:31]
	s_add_u32 s30, s30, 0x6000
	s_addc_u32 s31, s31, 0
	s_waitcnt vmcnt(31)
	v_fmac_f32_e32 v14, v138, v90
	v_fmac_f32_e32 v15, v158, v90
	global_load_dword v90, v52, s[30:31]
	s_add_u32 s30, s30, 0x6000
	s_addc_u32 s31, s31, 0
	s_waitcnt vmcnt(31)
	v_fmac_f32_e32 v14, v139, v91
	v_fmac_f32_e32 v15, v159, v91
	global_load_dword v91, v52, s[30:31]
	s_add_u32 s30, s30, 0x6000
	s_addc_u32 s31, s31, 0
	s_waitcnt vmcnt(31)
	v_fmac_f32_e32 v14, v140, v92
	v_fmac_f32_e32 v15, v160, v92
	global_load_dword v92, v52, s[30:31]
	s_add_u32 s30, s30, 0x6000
	s_addc_u32 s31, s31, 0
	s_waitcnt vmcnt(31)
	v_fmac_f32_e32 v14, v141, v93
	v_fmac_f32_e32 v15, v161, v93
	global_load_dword v93, v52, s[30:31]
	s_add_u32 s30, s30, 0x6000
	s_addc_u32 s31, s31, 0
	s_waitcnt vmcnt(31)
	v_fmac_f32_e32 v14, v142, v94
	v_fmac_f32_e32 v15, v162, v94
	global_load_dword v94, v52, s[30:31]
	s_add_u32 s30, s30, 0x6000
	s_addc_u32 s31, s31, 0
	s_waitcnt vmcnt(31)
	v_fmac_f32_e32 v14, v143, v95
	v_fmac_f32_e32 v15, v163, v95
	global_load_dword v95, v52, s[30:31]
	s_add_u32 s30, s30, 0x6000
	s_addc_u32 s31, s31, 0
	ds_read_b128 v[128:131], v17 offset:192
	ds_read_b128 v[132:135], v17 offset:208
	ds_read_b128 v[136:139], v17 offset:224
	ds_read_b128 v[140:143], v17 offset:240
	ds_read_b128 v[148:151], v17 offset:4288
	ds_read_b128 v[152:155], v17 offset:4304
	ds_read_b128 v[156:159], v17 offset:4320
	ds_read_b128 v[160:163], v17 offset:4336
	s_waitcnt lgkmcnt(8)
	s_waitcnt vmcnt(31)
	v_fmac_f32_e32 v14, v96, v64
	v_fmac_f32_e32 v15, v112, v64
	global_load_dword v64, v52, s[30:31]
	s_add_u32 s30, s30, 0x6000
	s_addc_u32 s31, s31, 0
	s_waitcnt vmcnt(31)
	v_fmac_f32_e32 v14, v97, v65
	v_fmac_f32_e32 v15, v113, v65
	global_load_dword v65, v52, s[30:31]
	s_add_u32 s30, s30, 0x6000
	s_addc_u32 s31, s31, 0
	s_waitcnt vmcnt(31)
	v_fmac_f32_e32 v14, v98, v66
	v_fmac_f32_e32 v15, v114, v66
	global_load_dword v66, v52, s[30:31]
	s_add_u32 s30, s30, 0x6000
	s_addc_u32 s31, s31, 0
	s_waitcnt vmcnt(31)
	v_fmac_f32_e32 v14, v99, v67
	v_fmac_f32_e32 v15, v115, v67
	global_load_dword v67, v52, s[30:31]
	s_add_u32 s30, s30, 0x6000
	s_addc_u32 s31, s31, 0
	s_waitcnt vmcnt(31)
	v_fmac_f32_e32 v14, v100, v68
	v_fmac_f32_e32 v15, v116, v68
	global_load_dword v68, v52, s[30:31]
	s_add_u32 s30, s30, 0x6000
	s_addc_u32 s31, s31, 0
	s_waitcnt vmcnt(31)
	v_fmac_f32_e32 v14, v101, v69
	v_fmac_f32_e32 v15, v117, v69
	global_load_dword v69, v52, s[30:31]
	s_add_u32 s30, s30, 0x6000
	s_addc_u32 s31, s31, 0
	s_waitcnt vmcnt(31)
	v_fmac_f32_e32 v14, v102, v70
	v_fmac_f32_e32 v15, v118, v70
	global_load_dword v70, v52, s[30:31]
	s_add_u32 s30, s30, 0x6000
	s_addc_u32 s31, s31, 0
	s_waitcnt vmcnt(31)
	v_fmac_f32_e32 v14, v103, v71
	v_fmac_f32_e32 v15, v119, v71
	global_load_dword v71, v52, s[30:31]
	s_add_u32 s30, s30, 0x6000
	s_addc_u32 s31, s31, 0
	s_waitcnt vmcnt(31)
; template <class PT> __device__ __forceinline__ void setup_phase(const PT& P, float* X, float* MOD, float* ROPE, float* LB, float* SCAL, char* lds) {
;     ...
; #pragma unroll 8
;       for (int k = 0; k < 128; ++k) { const float wv = w[(size_t)k * 6144]; a0 = fmaf(sv[wid * 128 + k], wv, a0); a1 = fmaf(sv[1024 + wid * 128 + k], wv, a1); }
	v_fmac_f32_e32 v14, v104, v72
	v_fmac_f32_e32 v15, v120, v72
	global_load_dword v72, v52, s[30:31]
	s_add_u32 s30, s30, 0x6000
	s_addc_u32 s31, s31, 0
	s_waitcnt vmcnt(31)
	v_fmac_f32_e32 v14, v105, v73
	v_fmac_f32_e32 v15, v121, v73
	global_load_dword v73, v52, s[30:31]
	s_add_u32 s30, s30, 0x6000
	s_addc_u32 s31, s31, 0
	s_waitcnt vmcnt(31)
	v_fmac_f32_e32 v14, v106, v74
	v_fmac_f32_e32 v15, v122, v74
	global_load_dword v74, v52, s[30:31]
	s_add_u32 s30, s30, 0x6000
	s_addc_u32 s31, s31, 0
	s_waitcnt vmcnt(31)
	v_fmac_f32_e32 v14, v107, v75
	v_fmac_f32_e32 v15, v123, v75
	global_load_dword v75, v52, s[30:31]
	s_add_u32 s30, s30, 0x6000
	s_addc_u32 s31, s31, 0
	s_waitcnt vmcnt(31)
	v_fmac_f32_e32 v14, v108, v76
	v_fmac_f32_e32 v15, v124, v76
	global_load_dword v76, v52, s[30:31]
	s_add_u32 s30, s30, 0x6000
	s_addc_u32 s31, s31, 0
	s_waitcnt vmcnt(31)
	v_fmac_f32_e32 v14, v109, v77
	v_fmac_f32_e32 v15, v125, v77
	global_load_dword v77, v52, s[30:31]
	s_add_u32 s30, s30, 0x6000
	s_addc_u32 s31, s31, 0
	s_waitcnt vmcnt(31)
	v_fmac_f32_e32 v14, v110, v78
	v_fmac_f32_e32 v15, v126, v78
	global_load_dword v78, v52, s[30:31]
	s_add_u32 s30, s30, 0x6000
	s_addc_u32 s31, s31, 0
	s_waitcnt vmcnt(31)
	v_fmac_f32_e32 v14, v111, v79
	v_fmac_f32_e32 v15, v127, v79
	global_load_dword v79, v52, s[30:31]
	s_add_u32 s30, s30, 0x6000
	s_addc_u32 s31, s31, 0
	ds_read_b128 v[96:99], v17 offset:256
	ds_read_b128 v[100:103], v17 offset:272
	ds_read_b128 v[104:107], v17 offset:288
	ds_read_b128 v[108:111], v17 offset:304
	ds_read_b128 v[112:115], v17 offset:4352
	ds_read_b128 v[116:119], v17 offset:4368
	ds_read_b128 v[120:123], v17 offset:4384
	ds_read_b128 v[124:127], v17 offset:4400
	s_waitcnt lgkmcnt(8)
	s_waitcnt vmcnt(31)
	v_fmac_f32_e32 v14, v128, v80
	v_fmac_f32_e32 v15, v148, v80
	global_load_dword v80, v52, s[30:31]
	s_add_u32 s30, s30, 0x6000
	s_addc_u32 s31, s31, 0
	s_waitcnt vmcnt(31)
	v_fmac_f32_e32 v14, v129, v81
	v_fmac_f32_e32 v15, v149, v81
	global_load_dword v81, v52, s[30:31]
	s_add_u32 s30, s30, 0x6000
	s_addc_u32 s31, s31, 0
	s_waitcnt vmcnt(31)
	v_fmac_f32_e32 v14, v130, v82
	v_fmac_f32_e32 v15, v150, v82
	global_load_dword v82, v52, s[30:31]
	s_add_u32 s30, s30, 0x6000
	s_addc_u32 s31, s31, 0
	s_waitcnt vmcnt(31)
	v_fmac_f32_e32 v14, v131, v83
	v_fmac_f32_e32 v15, v151, v83
	global_load_dword v83, v52, s[30:31]
	s_add_u32 s30, s30, 0x6000
	s_addc_u32 s31, s31, 0
	s_waitcnt vmcnt(31)
	v_fmac_f32_e32 v14, v132, v84
	v_fmac_f32_e32 v15, v152, v84
	global_load_dword v84, v52, s[30:31]
	s_add_u32 s30, s30, 0x6000
	s_addc_u32 s31, s31, 0
	s_waitcnt vmcnt(31)
	v_fmac_f32_e32 v14, v133, v85
	v_fmac_f32_e32 v15, v153, v85
	global_load_dword v85, v52, s[30:31]
	s_add_u32 s30, s30, 0x6000
	s_addc_u32 s31, s31, 0
	s_waitcnt vmcnt(31)
	v_fmac_f32_e32 v14, v134, v86
	v_fmac_f32_e32 v15, v154, v86
	global_load_dword v86, v52, s[30:31]
	s_add_u32 s30, s30, 0x6000
	s_addc_u32 s31, s31, 0
	s_waitcnt vmcnt(31)
	v_fmac_f32_e32 v14, v135, v87
	v_fmac_f32_e32 v15, v155, v87
	global_load_dword v87, v52, s[30:31]
	s_add_u32 s30, s30, 0x6000
	s_addc_u32 s31, s31, 0
	s_waitcnt vmcnt(31)
	v_fmac_f32_e32 v14, v136, v88
	v_fmac_f32_e32 v15, v156, v88
	global_load_dword v88, v52, s[30:31]
	s_add_u32 s30, s30, 0x6000
	s_addc_u32 s31, s31, 0
	s_waitcnt vmcnt(31)
	v_fmac_f32_e32 v14, v137, v89
	v_fmac_f32_e32 v15, v157, v89
	global_load_dword v89, v52, s[30:31]
	s_add_u32 s30, s30, 0x6000
	s_addc_u32 s31, s31, 0
	s_waitcnt vmcnt(31)
	v_fmac_f32_e32 v14, v138, v90
	v_fmac_f32_e32 v15, v158, v90
	global_load_dword v90, v52, s[30:31]
	s_add_u32 s30, s30, 0x6000
	s_addc_u32 s31, s31, 0
	s_waitcnt vmcnt(31)
	v_fmac_f32_e32 v14, v139, v91
	v_fmac_f32_e32 v15, v159, v91
	global_load_dword v91, v52, s[30:31]
	s_add_u32 s30, s30, 0x6000
	s_addc_u32 s31, s31, 0
	s_waitcnt vmcnt(31)
	v_fmac_f32_e32 v14, v140, v92
	v_fmac_f32_e32 v15, v160, v92
	global_load_dword v92, v52, s[30:31]
	s_add_u32 s30, s30, 0x6000
	s_addc_u32 s31, s31, 0
	s_waitcnt vmcnt(31)
	v_fmac_f32_e32 v14, v141, v93
	v_fmac_f32_e32 v15, v161, v93
	global_load_dword v93, v52, s[30:31]
	s_add_u32 s30, s30, 0x6000
	s_addc_u32 s31, s31, 0
	s_waitcnt vmcnt(31)
	v_fmac_f32_e32 v14, v142, v94
	v_fmac_f32_e32 v15, v162, v94
	global_load_dword v94, v52, s[30:31]
	s_add_u32 s30, s30, 0x6000
	s_addc_u32 s31, s31, 0
	s_waitcnt vmcnt(31)
	v_fmac_f32_e32 v14, v143, v95
	v_fmac_f32_e32 v15, v163, v95
	global_load_dword v95, v52, s[30:31]
	s_add_u32 s30, s30, 0x6000
	s_addc_u32 s31, s31, 0
	ds_read_b128 v[128:131], v17 offset:320
	ds_read_b128 v[132:135], v17 offset:336
	ds_read_b128 v[136:139], v17 offset:352
	ds_read_b128 v[140:143], v17 offset:368
	ds_read_b128 v[148:151], v17 offset:4416
	ds_read_b128 v[152:155], v17 offset:4432
	ds_read_b128 v[156:159], v17 offset:4448
	ds_read_b128 v[160:163], v17 offset:4464
	s_waitcnt lgkmcnt(8)
	s_waitcnt vmcnt(31)
	v_fmac_f32_e32 v14, v96, v64
	v_fmac_f32_e32 v15, v112, v64
	global_load_dword v64, v52, s[30:31]
	s_add_u32 s30, s30, 0x6000
	s_addc_u32 s31, s31, 0
	s_waitcnt vmcnt(31)
	v_fmac_f32_e32 v14, v97, v65
	v_fmac_f32_e32 v15, v113, v65
	global_load_dword v65, v52, s[30:31]
	s_add_u32 s30, s30, 0x6000
	s_addc_u32 s31, s31, 0
	s_waitcnt vmcnt(31)
	v_fmac_f32_e32 v14, v98, v66
	v_fmac_f32_e32 v15, v114, v66
	global_load_dword v66, v52, s[30:31]
	s_add_u32 s30, s30, 0x6000
	s_addc_u32 s31, s31, 0
	s_waitcnt vmcnt(31)
	v_fmac_f32_e32 v14, v99, v67
	v_fmac_f32_e32 v15, v115, v67
	global_load_dword v67, v52, s[30:31]
	s_add_u32 s30, s30, 0x6000
	s_addc_u32 s31, s31, 0
	s_waitcnt vmcnt(31)
	v_fmac_f32_e32 v14, v100, v68
	v_fmac_f32_e32 v15, v116, v68
	global_load_dword v68, v52, s[30:31]
	s_add_u32 s30, s30, 0x6000
	s_addc_u32 s31, s31, 0
	s_waitcnt vmcnt(31)
; template <class PT> __device__ __forceinline__ void setup_phase(const PT& P, float* X, float* MOD, float* ROPE, float* LB, float* SCAL, char* lds) {
;     ...
; #pragma unroll 8
;       for (int k = 0; k < 128; ++k) { const float wv = w[(size_t)k * 6144]; a0 = fmaf(sv[wid * 128 + k], wv, a0); a1 = fmaf(sv[1024 + wid * 128 + k], wv, a1); }
	v_fmac_f32_e32 v14, v101, v69
	v_fmac_f32_e32 v15, v117, v69
	global_load_dword v69, v52, s[30:31]
	s_add_u32 s30, s30, 0x6000
	s_addc_u32 s31, s31, 0
	s_waitcnt vmcnt(31)
	v_fmac_f32_e32 v14, v102, v70
	v_fmac_f32_e32 v15, v118, v70
	global_load_dword v70, v52, s[30:31]
	s_add_u32 s30, s30, 0x6000
	s_addc_u32 s31, s31, 0
	s_waitcnt vmcnt(31)
	v_fmac_f32_e32 v14, v103, v71
	v_fmac_f32_e32 v15, v119, v71
	global_load_dword v71, v52, s[30:31]
	s_add_u32 s30, s30, 0x6000
	s_addc_u32 s31, s31, 0
	s_waitcnt vmcnt(31)
	v_fmac_f32_e32 v14, v104, v72
	v_fmac_f32_e32 v15, v120, v72
	global_load_dword v72, v52, s[30:31]
	s_add_u32 s30, s30, 0x6000
	s_addc_u32 s31, s31, 0
	s_waitcnt vmcnt(31)
	v_fmac_f32_e32 v14, v105, v73
	v_fmac_f32_e32 v15, v121, v73
	global_load_dword v73, v52, s[30:31]
	s_add_u32 s30, s30, 0x6000
	s_addc_u32 s31, s31, 0
	s_waitcnt vmcnt(31)
	v_fmac_f32_e32 v14, v106, v74
	v_fmac_f32_e32 v15, v122, v74
	global_load_dword v74, v52, s[30:31]
	s_add_u32 s30, s30, 0x6000
	s_addc_u32 s31, s31, 0
	s_waitcnt vmcnt(31)
	v_fmac_f32_e32 v14, v107, v75
	v_fmac_f32_e32 v15, v123, v75
	global_load_dword v75, v52, s[30:31]
	s_add_u32 s30, s30, 0x6000
	s_addc_u32 s31, s31, 0
	s_waitcnt vmcnt(31)
	v_fmac_f32_e32 v14, v108, v76
	v_fmac_f32_e32 v15, v124, v76
	global_load_dword v76, v52, s[30:31]
	s_add_u32 s30, s30, 0x6000
	s_addc_u32 s31, s31, 0
	s_waitcnt vmcnt(31)
	v_fmac_f32_e32 v14, v109, v77
	v_fmac_f32_e32 v15, v125, v77
	global_load_dword v77, v52, s[30:31]
	s_add_u32 s30, s30, 0x6000
	s_addc_u32 s31, s31, 0
	s_waitcnt vmcnt(31)
	v_fmac_f32_e32 v14, v110, v78
	v_fmac_f32_e32 v15, v126, v78
	global_load_dword v78, v52, s[30:31]
	s_add_u32 s30, s30, 0x6000
	s_addc_u32 s31, s31, 0
	s_waitcnt vmcnt(31)
	v_fmac_f32_e32 v14, v111, v79
	v_fmac_f32_e32 v15, v127, v79
	global_load_dword v79, v52, s[30:31]
	s_add_u32 s30, s30, 0x6000
	s_addc_u32 s31, s31, 0
	ds_read_b128 v[96:99], v17 offset:384
	ds_read_b128 v[100:103], v17 offset:400
	ds_read_b128 v[104:107], v17 offset:416
	ds_read_b128 v[108:111], v17 offset:432
	ds_read_b128 v[112:115], v17 offset:4480
	ds_read_b128 v[116:119], v17 offset:4496
	ds_read_b128 v[120:123], v17 offset:4512
	ds_read_b128 v[124:127], v17 offset:4528
	s_waitcnt lgkmcnt(8)
	s_waitcnt vmcnt(31)
	v_fmac_f32_e32 v14, v128, v80
	v_fmac_f32_e32 v15, v148, v80
	global_load_dword v80, v52, s[30:31]
	s_add_u32 s30, s30, 0x6000
	s_addc_u32 s31, s31, 0
	s_waitcnt vmcnt(31)
	v_fmac_f32_e32 v14, v129, v81
	v_fmac_f32_e32 v15, v149, v81
	global_load_dword v81, v52, s[30:31]
	s_add_u32 s30, s30, 0x6000
	s_addc_u32 s31, s31, 0
	s_waitcnt vmcnt(31)
	v_fmac_f32_e32 v14, v130, v82
	v_fmac_f32_e32 v15, v150, v82
	global_load_dword v82, v52, s[30:31]
	s_add_u32 s30, s30, 0x6000
	s_addc_u32 s31, s31, 0
	s_waitcnt vmcnt(31)
	v_fmac_f32_e32 v14, v131, v83
	v_fmac_f32_e32 v15, v151, v83
	global_load_dword v83, v52, s[30:31]
	s_add_u32 s30, s30, 0x6000
	s_addc_u32 s31, s31, 0
	s_waitcnt vmcnt(31)
	v_fmac_f32_e32 v14, v132, v84
	v_fmac_f32_e32 v15, v152, v84
	global_load_dword v84, v52, s[30:31]
	s_add_u32 s30, s30, 0x6000
	s_addc_u32 s31, s31, 0
	s_waitcnt vmcnt(31)
	v_fmac_f32_e32 v14, v133, v85
	v_fmac_f32_e32 v15, v153, v85
	global_load_dword v85, v52, s[30:31]
	s_add_u32 s30, s30, 0x6000
	s_addc_u32 s31, s31, 0
	s_waitcnt vmcnt(31)
	v_fmac_f32_e32 v14, v134, v86
	v_fmac_f32_e32 v15, v154, v86
	global_load_dword v86, v52, s[30:31]
	s_add_u32 s30, s30, 0x6000
	s_addc_u32 s31, s31, 0
	s_waitcnt vmcnt(31)
	v_fmac_f32_e32 v14, v135, v87
	v_fmac_f32_e32 v15, v155, v87
	global_load_dword v87, v52, s[30:31]
	s_add_u32 s30, s30, 0x6000
	s_addc_u32 s31, s31, 0
	s_waitcnt vmcnt(31)
	v_fmac_f32_e32 v14, v136, v88
	v_fmac_f32_e32 v15, v156, v88
	global_load_dword v88, v52, s[30:31]
	s_add_u32 s30, s30, 0x6000
	s_addc_u32 s31, s31, 0
	s_waitcnt vmcnt(31)
	v_fmac_f32_e32 v14, v137, v89
	v_fmac_f32_e32 v15, v157, v89
	global_load_dword v89, v52, s[30:31]
	s_add_u32 s30, s30, 0x6000
	s_addc_u32 s31, s31, 0
	s_waitcnt vmcnt(31)
	v_fmac_f32_e32 v14, v138, v90
	v_fmac_f32_e32 v15, v158, v90
	global_load_dword v90, v52, s[30:31]
	s_add_u32 s30, s30, 0x6000
	s_addc_u32 s31, s31, 0
	s_waitcnt vmcnt(31)
	v_fmac_f32_e32 v14, v139, v91
	v_fmac_f32_e32 v15, v159, v91
	global_load_dword v91, v52, s[30:31]
	s_add_u32 s30, s30, 0x6000
	s_addc_u32 s31, s31, 0
	s_waitcnt vmcnt(31)
	v_fmac_f32_e32 v14, v140, v92
	v_fmac_f32_e32 v15, v160, v92
	global_load_dword v92, v52, s[30:31]
	s_add_u32 s30, s30, 0x6000
	s_addc_u32 s31, s31, 0
	s_waitcnt vmcnt(31)
; #define P (*get_params())
; template <class PT> __device__ __forceinline__ void setup_phase(const PT& P, float* X, float* MOD, float* ROPE, float* LB, float* SCAL, char* lds) {
;     ...
; #pragma unroll 8
;       for (int k = 0; k < 128; ++k) { const float wv = w[(size_t)k * 6144]; a0 = fmaf(sv[wid * 128 + k], wv, a0); a1 = fmaf(sv[1024 + wid * 128 + k], wv, a1); }
;       red[(wid * 2 + 0) * 64 + lane] = a0; red[(wid * 2 + 1) * 64 + lane] = a1;
;       __syncthreads();
;       if (wid < 2) { float s = P.ada_b[l * 6144 + n];
; #pragma unroll
;         for (int w8 = 0; w8 < 8; ++w8) s += red[(w8 * 2 + wid) * 64 + lane];
;         MOD[((size_t)l * 2 + wid) * 6144 + n] = s; }
;       __syncthreads();
	v_fmac_f32_e32 v14, v141, v93
	v_fmac_f32_e32 v15, v161, v93
	global_load_dword v93, v52, s[30:31]
	s_add_u32 s30, s30, 0x6000
	s_addc_u32 s31, s31, 0
	s_waitcnt vmcnt(31)
	v_fmac_f32_e32 v14, v142, v94
	v_fmac_f32_e32 v15, v162, v94
	global_load_dword v94, v52, s[30:31]
	s_add_u32 s30, s30, 0x6000
	s_addc_u32 s31, s31, 0
	s_waitcnt vmcnt(31)
	v_fmac_f32_e32 v14, v143, v95
	v_fmac_f32_e32 v15, v163, v95
	global_load_dword v95, v52, s[30:31]
	s_add_u32 s30, s30, 0x6000
	s_addc_u32 s31, s31, 0
	ds_read_b128 v[128:131], v17 offset:448
	ds_read_b128 v[132:135], v17 offset:464
	ds_read_b128 v[136:139], v17 offset:480
	ds_read_b128 v[140:143], v17 offset:496
	ds_read_b128 v[148:151], v17 offset:4544
	ds_read_b128 v[152:155], v17 offset:4560
	ds_read_b128 v[156:159], v17 offset:4576
	ds_read_b128 v[160:163], v17 offset:4592
	s_waitcnt lgkmcnt(8)
	s_waitcnt vmcnt(31)
	v_fmac_f32_e32 v14, v96, v64
	v_fmac_f32_e32 v15, v112, v64
	s_waitcnt vmcnt(30)
	v_fmac_f32_e32 v14, v97, v65
	v_fmac_f32_e32 v15, v113, v65
	s_waitcnt vmcnt(29)
	v_fmac_f32_e32 v14, v98, v66
	v_fmac_f32_e32 v15, v114, v66
	s_waitcnt vmcnt(28)
	v_fmac_f32_e32 v14, v99, v67
	v_fmac_f32_e32 v15, v115, v67
	s_waitcnt vmcnt(27)
	v_fmac_f32_e32 v14, v100, v68
	v_fmac_f32_e32 v15, v116, v68
	s_waitcnt vmcnt(26)
	v_fmac_f32_e32 v14, v101, v69
	v_fmac_f32_e32 v15, v117, v69
	s_waitcnt vmcnt(25)
	v_fmac_f32_e32 v14, v102, v70
	v_fmac_f32_e32 v15, v118, v70
	s_waitcnt vmcnt(24)
	v_fmac_f32_e32 v14, v103, v71
	v_fmac_f32_e32 v15, v119, v71
	s_waitcnt vmcnt(23)
	v_fmac_f32_e32 v14, v104, v72
	v_fmac_f32_e32 v15, v120, v72
	s_waitcnt vmcnt(22)
	v_fmac_f32_e32 v14, v105, v73
	v_fmac_f32_e32 v15, v121, v73
	s_waitcnt vmcnt(21)
	v_fmac_f32_e32 v14, v106, v74
	v_fmac_f32_e32 v15, v122, v74
	s_waitcnt vmcnt(20)
	v_fmac_f32_e32 v14, v107, v75
	v_fmac_f32_e32 v15, v123, v75
	s_waitcnt vmcnt(19)
	v_fmac_f32_e32 v14, v108, v76
	v_fmac_f32_e32 v15, v124, v76
	s_waitcnt vmcnt(18)
	v_fmac_f32_e32 v14, v109, v77
	v_fmac_f32_e32 v15, v125, v77
	s_waitcnt vmcnt(17)
	v_fmac_f32_e32 v14, v110, v78
	v_fmac_f32_e32 v15, v126, v78
	s_waitcnt vmcnt(16)
	v_fmac_f32_e32 v14, v111, v79
	v_fmac_f32_e32 v15, v127, v79
	s_waitcnt lgkmcnt(0)
	s_waitcnt vmcnt(15)
	v_fmac_f32_e32 v14, v128, v80
	v_fmac_f32_e32 v15, v148, v80
	s_waitcnt vmcnt(14)
	v_fmac_f32_e32 v14, v129, v81
	v_fmac_f32_e32 v15, v149, v81
	s_waitcnt vmcnt(13)
	v_fmac_f32_e32 v14, v130, v82
	v_fmac_f32_e32 v15, v150, v82
	s_waitcnt vmcnt(12)
	v_fmac_f32_e32 v14, v131, v83
	v_fmac_f32_e32 v15, v151, v83
	s_waitcnt vmcnt(11)
	v_fmac_f32_e32 v14, v132, v84
	v_fmac_f32_e32 v15, v152, v84
	s_waitcnt vmcnt(10)
	v_fmac_f32_e32 v14, v133, v85
	v_fmac_f32_e32 v15, v153, v85
	s_waitcnt vmcnt(9)
	v_fmac_f32_e32 v14, v134, v86
	v_fmac_f32_e32 v15, v154, v86
	s_waitcnt vmcnt(8)
	v_fmac_f32_e32 v14, v135, v87
	v_fmac_f32_e32 v15, v155, v87
	s_waitcnt vmcnt(7)
	v_fmac_f32_e32 v14, v136, v88
	v_fmac_f32_e32 v15, v156, v88
	s_waitcnt vmcnt(6)
	v_fmac_f32_e32 v14, v137, v89
	v_fmac_f32_e32 v15, v157, v89
	s_waitcnt vmcnt(5)
	v_fmac_f32_e32 v14, v138, v90
	v_fmac_f32_e32 v15, v158, v90
	s_waitcnt vmcnt(4)
	v_fmac_f32_e32 v14, v139, v91
	v_fmac_f32_e32 v15, v159, v91
	s_waitcnt vmcnt(3)
	v_fmac_f32_e32 v14, v140, v92
	v_fmac_f32_e32 v15, v160, v92
	s_waitcnt vmcnt(2)
	v_fmac_f32_e32 v14, v141, v93
	v_fmac_f32_e32 v15, v161, v93
	s_waitcnt vmcnt(1)
	v_fmac_f32_e32 v14, v142, v94
	v_fmac_f32_e32 v15, v162, v94
	s_waitcnt vmcnt(0)
	v_fmac_f32_e32 v14, v143, v95
	v_fmac_f32_e32 v15, v163, v95
	ds_write2st64_b32 v5, v14, v15 offset0:32 offset1:33
	s_waitcnt lgkmcnt(0)
	s_barrier
	s_and_saveexec_b64 s[24:25], s[6:7]
	s_cbranch_execz .LBB0_10
	s_mul_i32 s9, s8, 0x1800
	v_add_u32_e32 v12, s9, v10
	v_ashrrev_i32_e32 v13, 31, v12
	v_lshl_add_u64 v[12:13], v[12:13], 2, s[10:11]
	global_load_dword v17, v[12:13], off
	ds_read2st64_b32 v[12:13], v16 offset0:32 offset1:34
	ds_read2st64_b32 v[14:15], v16 offset0:36 offset1:38
	ds_read2st64_b32 v[18:19], v16 offset0:40 offset1:42
	ds_read2st64_b32 v[20:21], v16 offset0:44 offset1:46
	v_lshl_add_u32 v24, s8, 1, v4
	v_mov_b64_e32 v[22:23], s[20:21]
	v_mad_i64_i32 v[22:23], s[8:9], v24, s28, v[22:23]
	v_lshl_add_u64 v[10:11], v[10:11], 2, v[22:23]
	s_waitcnt vmcnt(0) lgkmcnt(3)
	v_add_f32_e32 v12, v17, v12
	v_add_f32_e32 v12, v12, v13
	s_waitcnt lgkmcnt(2)
	v_add_f32_e32 v12, v12, v14
	v_add_f32_e32 v12, v12, v15
	s_waitcnt lgkmcnt(1)
	v_add_f32_e32 v12, v12, v18
	v_add_f32_e32 v12, v12, v19
	s_waitcnt lgkmcnt(0)
	v_add_f32_e32 v12, v12, v20
	v_add_f32_e32 v12, v12, v21
	global_store_dword v[10:11], v12, off
	s_branch .LBB0_10
